# hyena stage-2 loop: 48 conv-tap loads issued together up front plus next-trip line touches (counted wait), on top of previous version
# baseline (speedup 1.0000x reference)
; DI void hyena_item(const Params& p, int l, int dpr, LAS unsigned char* lds) {
;     ...
; #pragma unroll 4
;     for (int r = 0; r < 16; ++r) { const int t = tid + NTHR * r; const hc y0 = X0[XI(t)], y1 = X1[XI(t)];
;         const float yv[4] = {(float)y0.x, (float)y0.y, (float)y1.x, (float)y1.y};
;         float z[4];
; #pragma unroll
;         for (int c = 0; c < 4; ++c) z[c] = yv[c] * (1.0f / 64.0f) * conv3(bint + (size_t)(1024 + a + c) * S, t, w[c][0], w[c][1], w[c][2]) * 0.25f;
;         X0[XI(t)] = (hc){(_Float16)z[0], (_Float16)z[1]}; X1[XI(t)] = (hc){(_Float16)z[2], (_Float16)z[3]};
;         X0[XI(t + 8192)] = hzero; X1[XI(t + 8192)] = hzero; }
;     __syncthreads();
.LBB0_699:
	v_add_u32_e32 v16, s74, v12
	v_mov_b32_e32 v149, 0
	v_mov_b32_e32 v151, 0
	v_mov_b32_e32 v153, 0
	v_mov_b32_e32 v148, v16
	v_max_i32_e32 v150, 1, v148
	v_min_i32_e32 v152, 0x1ffe, v148
	v_lshlrev_b32_e32 v148, 2, v148
	v_lshlrev_b32_e32 v150, 2, v150
	v_lshlrev_b32_e32 v152, 2, v152
	v_lshl_add_u64 v[154:155], s[26:27], 0, v[148:149]
	global_load_dword v100, v[154:155], off
	v_lshl_add_u64 v[154:155], s[26:27], 0, v[150:151]
	global_load_dword v101, v[154:155], off offset:-4
	v_lshl_add_u64 v[154:155], s[26:27], 0, v[152:153]
	global_load_dword v102, v[154:155], off offset:4
	v_lshl_add_u64 v[154:155], s[22:23], 0, v[148:149]
	global_load_dword v103, v[154:155], off
	v_lshl_add_u64 v[154:155], s[22:23], 0, v[150:151]
	global_load_dword v104, v[154:155], off offset:-4
	v_lshl_add_u64 v[154:155], s[22:23], 0, v[152:153]
	global_load_dword v105, v[154:155], off offset:4
	v_lshl_add_u64 v[154:155], s[20:21], 0, v[148:149]
	global_load_dword v106, v[154:155], off
	v_lshl_add_u64 v[154:155], s[20:21], 0, v[150:151]
	global_load_dword v107, v[154:155], off offset:-4
	v_lshl_add_u64 v[154:155], s[20:21], 0, v[152:153]
	global_load_dword v108, v[154:155], off offset:4
	v_lshl_add_u64 v[154:155], s[24:25], 0, v[148:149]
	global_load_dword v109, v[154:155], off
	v_lshl_add_u64 v[154:155], s[24:25], 0, v[150:151]
	global_load_dword v110, v[154:155], off offset:-4
	v_lshl_add_u64 v[154:155], s[24:25], 0, v[152:153]
	global_load_dword v111, v[154:155], off offset:4
	v_add_u32_e32 v148, 0x200, v16
	v_max_i32_e32 v150, 1, v148
	v_min_i32_e32 v152, 0x1ffe, v148
	v_lshlrev_b32_e32 v148, 2, v148
	v_lshlrev_b32_e32 v150, 2, v150
	v_lshlrev_b32_e32 v152, 2, v152
	v_lshl_add_u64 v[154:155], s[26:27], 0, v[148:149]
	global_load_dword v112, v[154:155], off
	v_lshl_add_u64 v[154:155], s[26:27], 0, v[150:151]
	global_load_dword v113, v[154:155], off offset:-4
	v_lshl_add_u64 v[154:155], s[26:27], 0, v[152:153]
	global_load_dword v114, v[154:155], off offset:4
	v_lshl_add_u64 v[154:155], s[22:23], 0, v[148:149]
	global_load_dword v115, v[154:155], off
	v_lshl_add_u64 v[154:155], s[22:23], 0, v[150:151]
	global_load_dword v116, v[154:155], off offset:-4
	v_lshl_add_u64 v[154:155], s[22:23], 0, v[152:153]
	global_load_dword v117, v[154:155], off offset:4
	v_lshl_add_u64 v[154:155], s[20:21], 0, v[148:149]
	global_load_dword v118, v[154:155], off
	v_lshl_add_u64 v[154:155], s[20:21], 0, v[150:151]
	global_load_dword v119, v[154:155], off offset:-4
	v_lshl_add_u64 v[154:155], s[20:21], 0, v[152:153]
	global_load_dword v120, v[154:155], off offset:4
	v_lshl_add_u64 v[154:155], s[24:25], 0, v[148:149]
	global_load_dword v121, v[154:155], off
	v_lshl_add_u64 v[154:155], s[24:25], 0, v[150:151]
	global_load_dword v122, v[154:155], off offset:-4
	v_lshl_add_u64 v[154:155], s[24:25], 0, v[152:153]
	global_load_dword v123, v[154:155], off offset:4
	v_add_u32_e32 v148, 0x400, v16
	v_max_i32_e32 v150, 1, v148
	v_min_i32_e32 v152, 0x1ffe, v148
	v_lshlrev_b32_e32 v148, 2, v148
	v_lshlrev_b32_e32 v150, 2, v150
	v_lshlrev_b32_e32 v152, 2, v152
	v_lshl_add_u64 v[154:155], s[26:27], 0, v[148:149]
	global_load_dword v124, v[154:155], off
	v_lshl_add_u64 v[154:155], s[26:27], 0, v[150:151]
	global_load_dword v125, v[154:155], off offset:-4
	v_lshl_add_u64 v[154:155], s[26:27], 0, v[152:153]
	global_load_dword v126, v[154:155], off offset:4
	v_lshl_add_u64 v[154:155], s[22:23], 0, v[148:149]
	global_load_dword v127, v[154:155], off
	v_lshl_add_u64 v[154:155], s[22:23], 0, v[150:151]
	global_load_dword v128, v[154:155], off offset:-4
	v_lshl_add_u64 v[154:155], s[22:23], 0, v[152:153]
	global_load_dword v129, v[154:155], off offset:4
	v_lshl_add_u64 v[154:155], s[20:21], 0, v[148:149]
	global_load_dword v130, v[154:155], off
	v_lshl_add_u64 v[154:155], s[20:21], 0, v[150:151]
	global_load_dword v131, v[154:155], off offset:-4
	v_lshl_add_u64 v[154:155], s[20:21], 0, v[152:153]
	global_load_dword v132, v[154:155], off offset:4
	v_lshl_add_u64 v[154:155], s[24:25], 0, v[148:149]
	global_load_dword v133, v[154:155], off
	v_lshl_add_u64 v[154:155], s[24:25], 0, v[150:151]
	global_load_dword v134, v[154:155], off offset:-4
	v_lshl_add_u64 v[154:155], s[24:25], 0, v[152:153]
	global_load_dword v135, v[154:155], off offset:4
	v_add_u32_e32 v148, 0x600, v16
	v_max_i32_e32 v150, 1, v148
	v_min_i32_e32 v152, 0x1ffe, v148
	v_lshlrev_b32_e32 v148, 2, v148
	v_lshlrev_b32_e32 v150, 2, v150
	v_lshlrev_b32_e32 v152, 2, v152
	v_lshl_add_u64 v[154:155], s[26:27], 0, v[148:149]
	global_load_dword v136, v[154:155], off
	v_lshl_add_u64 v[154:155], s[26:27], 0, v[150:151]
	global_load_dword v137, v[154:155], off offset:-4
	v_lshl_add_u64 v[154:155], s[26:27], 0, v[152:153]
	global_load_dword v138, v[154:155], off offset:4
	v_lshl_add_u64 v[154:155], s[22:23], 0, v[148:149]
	global_load_dword v139, v[154:155], off
	v_lshl_add_u64 v[154:155], s[22:23], 0, v[150:151]
	global_load_dword v140, v[154:155], off offset:-4
	v_lshl_add_u64 v[154:155], s[22:23], 0, v[152:153]
	global_load_dword v141, v[154:155], off offset:4
	v_lshl_add_u64 v[154:155], s[20:21], 0, v[148:149]
	global_load_dword v142, v[154:155], off
	v_lshl_add_u64 v[154:155], s[20:21], 0, v[150:151]
	global_load_dword v143, v[154:155], off offset:-4
	v_lshl_add_u64 v[154:155], s[20:21], 0, v[152:153]
	global_load_dword v144, v[154:155], off offset:4
	v_lshl_add_u64 v[154:155], s[24:25], 0, v[148:149]
	global_load_dword v145, v[154:155], off
	v_lshl_add_u64 v[154:155], s[24:25], 0, v[150:151]
	global_load_dword v146, v[154:155], off offset:-4
	v_lshl_add_u64 v[154:155], s[24:25], 0, v[152:153]
	global_load_dword v147, v[154:155], off offset:4
; DI void hyena_item(const Params& p, int l, int dpr, LAS unsigned char* lds) {
;     ...
; #pragma unroll 4
;     for (int r = 0; r < 16; ++r) { const int t = tid + NTHR * r; const hc y0 = X0[XI(t)], y1 = X1[XI(t)];
;         const float yv[4] = {(float)y0.x, (float)y0.y, (float)y1.x, (float)y1.y};
;         float z[4];
; #pragma unroll
;         for (int c = 0; c < 4; ++c) z[c] = yv[c] * (1.0f / 64.0f) * conv3(bint + (size_t)(1024 + a + c) * S, t, w[c][0], w[c][1], w[c][2]) * 0.25f;
;         X0[XI(t)] = (hc){(_Float16)z[0], (_Float16)z[1]}; X1[XI(t)] = (hc){(_Float16)z[2], (_Float16)z[3]};
;         X0[XI(t + 8192)] = hzero; X1[XI(t + 8192)] = hzero; }
;     __syncthreads();
	v_add_u32_e32 v156, 0x800, v16
	v_mov_b32_e32 v157, 0
	v_lshlrev_b32_e32 v156, 2, v156
	v_lshl_add_u64 v[158:159], s[26:27], 0, v[156:157]
	global_load_dword v160, v[158:159], off
	v_lshl_add_u64 v[158:159], s[22:23], 0, v[156:157]
	global_load_dword v161, v[158:159], off
	v_lshl_add_u64 v[158:159], s[20:21], 0, v[156:157]
	global_load_dword v162, v[158:159], off
	v_lshl_add_u64 v[158:159], s[24:25], 0, v[156:157]
	global_load_dword v163, v[158:159], off
	v_add_u32_e32 v156, 0xa00, v16
	v_mov_b32_e32 v157, 0
	v_lshlrev_b32_e32 v156, 2, v156
	v_lshl_add_u64 v[158:159], s[26:27], 0, v[156:157]
	global_load_dword v164, v[158:159], off
	v_lshl_add_u64 v[158:159], s[22:23], 0, v[156:157]
	global_load_dword v165, v[158:159], off
	v_lshl_add_u64 v[158:159], s[20:21], 0, v[156:157]
	global_load_dword v166, v[158:159], off
	v_lshl_add_u64 v[158:159], s[24:25], 0, v[156:157]
	global_load_dword v167, v[158:159], off
	v_add_u32_e32 v156, 0xc00, v16
	v_mov_b32_e32 v157, 0
	v_lshlrev_b32_e32 v156, 2, v156
	v_lshl_add_u64 v[158:159], s[26:27], 0, v[156:157]
	global_load_dword v168, v[158:159], off
	v_lshl_add_u64 v[158:159], s[22:23], 0, v[156:157]
	global_load_dword v169, v[158:159], off
	v_lshl_add_u64 v[158:159], s[20:21], 0, v[156:157]
	global_load_dword v170, v[158:159], off
	v_lshl_add_u64 v[158:159], s[24:25], 0, v[156:157]
	global_load_dword v171, v[158:159], off
	v_add_u32_e32 v156, 0xe00, v16
	v_mov_b32_e32 v157, 0
	v_lshlrev_b32_e32 v156, 2, v156
	v_lshl_add_u64 v[158:159], s[26:27], 0, v[156:157]
	global_load_dword v172, v[158:159], off
	v_lshl_add_u64 v[158:159], s[22:23], 0, v[156:157]
	global_load_dword v173, v[158:159], off
	v_lshl_add_u64 v[158:159], s[20:21], 0, v[156:157]
	global_load_dword v174, v[158:159], off
	v_lshl_add_u64 v[158:159], s[24:25], 0, v[156:157]
	global_load_dword v175, v[158:159], off
	s_waitcnt vmcnt(16)
	v_ashrrev_i32_e32 v13, 4, v16
	v_ashrrev_i32_e32 v17, 8, v16
	v_add_u32_e32 v13, v13, v17
	v_ashrrev_i32_e32 v17, 31, v16
	v_max_i32_e32 v96, 1, v16
	v_min_i32_e32 v18, 0x1ffe, v16
	v_ashrrev_i32_e32 v19, 31, v18
	v_lshlrev_b64 v[22:23], 2, v[16:17]
	v_lshlrev_b64 v[26:27], 2, v[96:97]
	v_lshl_add_u64 v[24:25], s[26:27], 0, v[22:23]
	v_lshl_add_u64 v[28:29], s[26:27], 0, v[26:27]
	v_lshlrev_b64 v[18:19], 2, v[18:19]
	v_mov_b32_e32 v24, v100
	v_lshl_add_u64 v[30:31], s[20:21], 0, v[26:27]
	v_mov_b32_e32 v17, v101
	v_lshl_add_u64 v[28:29], s[26:27], 0, v[18:19]
	v_mov_b32_e32 v34, v102
	v_lshl_add_u64 v[28:29], s[22:23], 0, v[22:23]
	v_mov_b32_e32 v25, v103
	v_lshl_add_u64 v[28:29], s[22:23], 0, v[26:27]
	v_mov_b32_e32 v35, v104
	v_lshl_add_u64 v[28:29], s[22:23], 0, v[18:19]
	v_mov_b32_e32 v36, v105
	v_lshl_add_u64 v[28:29], s[20:21], 0, v[22:23]
	v_lshl_add_u64 v[22:23], s[24:25], 0, v[22:23]
	v_mov_b32_e32 v28, v106
	v_add_lshl_u32 v13, v16, v13, 2
	v_mov_b32_e32 v37, v107
	v_mov_b32_e32 v29, v109
	v_lshl_add_u64 v[30:31], s[20:21], 0, v[18:19]
	v_lshl_add_u64 v[22:23], s[24:25], 0, v[26:27]
	v_mov_b32_e32 v30, v108
	v_lshl_add_u64 v[18:19], s[24:25], 0, v[18:19]
	v_mov_b32_e32 v31, v110
	v_mov_b32_e32 v38, v111
	v_add_u32_e32 v21, 0, v13
	ds_read_b32 v32, v21
	v_add_u32_e32 v13, s66, v13
	ds_read_b32 v33, v13
	v_cmp_lt_i32_e64 s[40:41], 0, v16
	v_cmp_gt_i32_e64 s[42:43], s29, v16
	s_waitcnt lgkmcnt(1)
	v_cvt_f32_f16_e32 v18, v32
	v_cvt_f32_f16_sdwa v19, v32 dst_sel:DWORD dst_unused:UNUSED_PAD src0_sel:WORD_1
	s_addk_i32 s74, 0x800
	s_cmpk_eq_i32 s74, 0x2000
	v_pk_mul_f32 v[18:19], v[18:19], s[38:39] op_sel_hi:[1,0]
	s_nop 0
	v_cndmask_b32_e64 v22, 0, v17, s[40:41]
	s_nop 0
	v_cndmask_b32_e64 v26, 0, v34, s[42:43]
	s_nop 0
	v_cndmask_b32_e64 v23, 0, v35, s[40:41]
	v_pk_mul_f32 v[22:23], v[0:1], v[22:23]
	s_nop 0
	v_cndmask_b32_e64 v27, 0, v36, s[42:43]
	v_pk_fma_f32 v[22:23], v[4:5], v[24:25], v[22:23]
	s_nop 0
	v_cndmask_b32_e64 v24, 0, v30, s[42:43]
	v_pk_fma_f32 v[22:23], v[8:9], v[26:27], v[22:23]
	s_nop 0
	v_cndmask_b32_e64 v25, 0, v38, s[42:43]
	v_pk_mul_f32 v[18:19], v[18:19], v[22:23]
	v_cndmask_b32_e64 v23, 0, v31, s[40:41]
	v_pk_mul_f32 v[18:19], v[18:19], s[76:77] op_sel_hi:[1,0]
	v_cndmask_b32_e64 v22, 0, v37, s[40:41]
	v_cvt_pk_f16_f32 v17, v18, v19
	s_waitcnt lgkmcnt(0)
	v_cvt_f32_f16_e32 v18, v33
	v_cvt_f32_f16_sdwa v19, v33 dst_sel:DWORD dst_unused:UNUSED_PAD src0_sel:WORD_1
	v_pk_mul_f32 v[22:23], v[2:3], v[22:23]
	ds_write_b32 v21, v17
	v_pk_fma_f32 v[22:23], v[6:7], v[28:29], v[22:23]
	v_pk_mul_f32 v[18:19], v[18:19], s[38:39] op_sel_hi:[1,0]
	v_pk_fma_f32 v[22:23], v[10:11], v[24:25], v[22:23]
	s_nop 0
	v_pk_mul_f32 v[18:19], v[18:19], v[22:23]
	s_nop 0
	v_pk_mul_f32 v[18:19], v[18:19], s[76:77] op_sel_hi:[1,0]
	s_nop 0
	v_cvt_pk_f16_f32 v17, v18, v19
	ds_write_b32 v13, v17
	v_add_u32_e32 v13, 0x2000, v16
	v_ashrrev_i32_e32 v17, 4, v13
	v_ashrrev_i32_e32 v13, 8, v13
	v_add_u32_e32 v13, v17, v13
	v_add_lshl_u32 v13, v16, v13, 2
	v_add_u32_e32 v18, 0x200, v16
	v_add_u32_e32 v17, 0, v13
	v_add_u32_e32 v13, s66, v13
	v_ashrrev_i32_e32 v19, 31, v18
	v_max_i32_e32 v96, 1, v18
	v_min_i32_e32 v22, 0x1ffe, v18
	ds_write_b32 v17, v97 offset:32768
	ds_write_b32 v13, v97 offset:32768
	v_ashrrev_i32_e32 v13, 4, v18
	v_ashrrev_i32_e32 v17, 8, v18
	v_cmp_lt_i32_e64 s[40:41], 0, v18
	v_cmp_gt_i32_e64 s[42:43], s29, v18
	v_ashrrev_i32_e32 v23, 31, v22
	v_lshlrev_b64 v[18:19], 2, v[18:19]
	v_lshlrev_b64 v[26:27], 2, v[96:97]
	v_lshl_add_u64 v[24:25], s[26:27], 0, v[18:19]
	v_lshl_add_u64 v[28:29], s[26:27], 0, v[26:27]
	v_lshlrev_b64 v[22:23], 2, v[22:23]
	v_mov_b32_e32 v24, v112
	v_lshl_add_u64 v[30:31], s[20:21], 0, v[26:27]
	v_mov_b32_e32 v33, v113
	v_lshl_add_u64 v[28:29], s[26:27], 0, v[22:23]
	v_mov_b32_e32 v34, v114
	v_lshl_add_u64 v[28:29], s[22:23], 0, v[18:19]
	v_mov_b32_e32 v25, v115
	v_lshl_add_u64 v[28:29], s[22:23], 0, v[26:27]
	v_mov_b32_e32 v35, v116
	v_lshl_add_u64 v[28:29], s[22:23], 0, v[22:23]
	v_mov_b32_e32 v36, v117
	v_lshl_add_u64 v[28:29], s[20:21], 0, v[18:19]
	v_lshl_add_u64 v[18:19], s[24:25], 0, v[18:19]
	v_mov_b32_e32 v28, v118
	v_add_u32_e32 v13, v13, v17
	v_mov_b32_e32 v37, v119
	v_mov_b32_e32 v29, v121
	v_lshl_add_u64 v[30:31], s[20:21], 0, v[22:23]
	v_lshl_add_u64 v[18:19], s[24:25], 0, v[26:27]
	v_mov_b32_e32 v30, v120
	v_add_lshl_u32 v13, v16, v13, 2
	v_mov_b32_e32 v31, v122
	v_lshl_add_u64 v[18:19], s[24:25], 0, v[22:23]
	v_mov_b32_e32 v38, v123
	v_add_u32_e32 v17, 0, v13
	ds_read_b32 v21, v17 offset:2048
	v_add_u32_e32 v13, s66, v13
	ds_read_b32 v32, v13 offset:2048
	s_waitcnt lgkmcnt(1)
; DI void hyena_item(const Params& p, int l, int dpr, LAS unsigned char* lds) {
;     ...
; #pragma unroll 4
;     for (int r = 0; r < 16; ++r) { const int t = tid + NTHR * r; const hc y0 = X0[XI(t)], y1 = X1[XI(t)];
;         const float yv[4] = {(float)y0.x, (float)y0.y, (float)y1.x, (float)y1.y};
;         float z[4];
; #pragma unroll
;         for (int c = 0; c < 4; ++c) z[c] = yv[c] * (1.0f / 64.0f) * conv3(bint + (size_t)(1024 + a + c) * S, t, w[c][0], w[c][1], w[c][2]) * 0.25f;
;         X0[XI(t)] = (hc){(_Float16)z[0], (_Float16)z[1]}; X1[XI(t)] = (hc){(_Float16)z[2], (_Float16)z[3]};
;         X0[XI(t + 8192)] = hzero; X1[XI(t + 8192)] = hzero; }
;     __syncthreads();
	v_cvt_f32_f16_e32 v18, v21
	v_cvt_f32_f16_sdwa v19, v21 dst_sel:DWORD dst_unused:UNUSED_PAD src0_sel:WORD_1
	v_pk_mul_f32 v[18:19], v[18:19], s[38:39] op_sel_hi:[1,0]
	s_nop 0
	v_cndmask_b32_e64 v22, 0, v33, s[40:41]
	s_nop 0
	v_cndmask_b32_e64 v26, 0, v34, s[42:43]
	s_nop 0
	v_cndmask_b32_e64 v23, 0, v35, s[40:41]
	v_pk_mul_f32 v[22:23], v[0:1], v[22:23]
	s_nop 0
	v_cndmask_b32_e64 v27, 0, v36, s[42:43]
	v_pk_fma_f32 v[22:23], v[4:5], v[24:25], v[22:23]
	s_nop 0
	v_cndmask_b32_e64 v24, 0, v30, s[42:43]
	v_pk_fma_f32 v[22:23], v[8:9], v[26:27], v[22:23]
	s_nop 0
	v_cndmask_b32_e64 v25, 0, v38, s[42:43]
	v_pk_mul_f32 v[18:19], v[18:19], v[22:23]
	v_cndmask_b32_e64 v23, 0, v31, s[40:41]
	v_pk_mul_f32 v[18:19], v[18:19], s[76:77] op_sel_hi:[1,0]
	v_cndmask_b32_e64 v22, 0, v37, s[40:41]
	v_cvt_pk_f16_f32 v18, v18, v19
	ds_write_b32 v17, v18 offset:2048
	s_waitcnt lgkmcnt(1)
	v_cvt_f32_f16_e32 v18, v32
	v_cvt_f32_f16_sdwa v19, v32 dst_sel:DWORD dst_unused:UNUSED_PAD src0_sel:WORD_1
	v_pk_mul_f32 v[22:23], v[2:3], v[22:23]
	v_pk_mul_f32 v[18:19], v[18:19], s[38:39] op_sel_hi:[1,0]
	v_pk_fma_f32 v[22:23], v[6:7], v[28:29], v[22:23]
	s_nop 0
	v_pk_fma_f32 v[22:23], v[10:11], v[24:25], v[22:23]
	s_nop 0
	v_pk_mul_f32 v[18:19], v[18:19], v[22:23]
	s_nop 0
	v_pk_mul_f32 v[18:19], v[18:19], s[76:77] op_sel_hi:[1,0]
	s_nop 0
	v_cvt_pk_f16_f32 v17, v18, v19
	ds_write_b32 v13, v17 offset:2048
	v_add_u32_e32 v13, 0x2200, v16
	v_ashrrev_i32_e32 v17, 4, v13
	v_ashrrev_i32_e32 v13, 8, v13
	v_add_u32_e32 v13, v17, v13
	v_add_lshl_u32 v13, v16, v13, 2
	v_add_u32_e32 v18, 0x400, v16
	v_add_u32_e32 v17, 0, v13
	v_add_u32_e32 v13, s66, v13
	v_ashrrev_i32_e32 v19, 31, v18
	v_max_i32_e32 v96, 1, v18
	v_min_i32_e32 v22, 0x1ffe, v18
	ds_write_b32 v17, v97 offset:34816
	ds_write_b32 v13, v97 offset:34816
	v_ashrrev_i32_e32 v13, 4, v18
	v_ashrrev_i32_e32 v17, 8, v18
	v_cmp_lt_i32_e64 s[40:41], 0, v18
	v_cmp_gt_i32_e64 s[42:43], s29, v18
	v_ashrrev_i32_e32 v23, 31, v22
	v_lshlrev_b64 v[18:19], 2, v[18:19]
	v_lshlrev_b64 v[26:27], 2, v[96:97]
	v_lshl_add_u64 v[24:25], s[26:27], 0, v[18:19]
	v_lshl_add_u64 v[28:29], s[26:27], 0, v[26:27]
	v_lshlrev_b64 v[22:23], 2, v[22:23]
	v_mov_b32_e32 v24, v124
	v_lshl_add_u64 v[30:31], s[20:21], 0, v[26:27]
	v_mov_b32_e32 v33, v125
	v_lshl_add_u64 v[28:29], s[26:27], 0, v[22:23]
	v_mov_b32_e32 v34, v126
	v_lshl_add_u64 v[28:29], s[22:23], 0, v[18:19]
	v_mov_b32_e32 v25, v127
	v_lshl_add_u64 v[28:29], s[22:23], 0, v[26:27]
	v_mov_b32_e32 v35, v128
	v_lshl_add_u64 v[28:29], s[22:23], 0, v[22:23]
	v_mov_b32_e32 v36, v129
	v_lshl_add_u64 v[28:29], s[20:21], 0, v[18:19]
	v_lshl_add_u64 v[18:19], s[24:25], 0, v[18:19]
	v_mov_b32_e32 v28, v130
	v_add_u32_e32 v13, v13, v17
	v_mov_b32_e32 v37, v131
	v_mov_b32_e32 v29, v133
	v_lshl_add_u64 v[30:31], s[20:21], 0, v[22:23]
	v_lshl_add_u64 v[18:19], s[24:25], 0, v[26:27]
	v_mov_b32_e32 v30, v132
	v_add_lshl_u32 v13, v16, v13, 2
	v_mov_b32_e32 v31, v134
	v_lshl_add_u64 v[18:19], s[24:25], 0, v[22:23]
	v_mov_b32_e32 v38, v135
	v_add_u32_e32 v17, 0, v13
	ds_read_b32 v21, v17 offset:4096
	v_add_u32_e32 v13, s66, v13
	ds_read_b32 v32, v13 offset:4096
	s_waitcnt lgkmcnt(1)
	v_cvt_f32_f16_e32 v18, v21
	v_cvt_f32_f16_sdwa v19, v21 dst_sel:DWORD dst_unused:UNUSED_PAD src0_sel:WORD_1
	v_pk_mul_f32 v[18:19], v[18:19], s[38:39] op_sel_hi:[1,0]
	s_nop 0
	v_cndmask_b32_e64 v22, 0, v33, s[40:41]
	s_nop 0
	v_cndmask_b32_e64 v26, 0, v34, s[42:43]
	s_nop 0
	v_cndmask_b32_e64 v23, 0, v35, s[40:41]
	v_pk_mul_f32 v[22:23], v[0:1], v[22:23]
	s_nop 0
	v_cndmask_b32_e64 v27, 0, v36, s[42:43]
	v_pk_fma_f32 v[22:23], v[4:5], v[24:25], v[22:23]
	s_nop 0
	v_cndmask_b32_e64 v24, 0, v30, s[42:43]
	v_pk_fma_f32 v[22:23], v[8:9], v[26:27], v[22:23]
	s_nop 0
	v_cndmask_b32_e64 v25, 0, v38, s[42:43]
	v_pk_mul_f32 v[18:19], v[18:19], v[22:23]
	v_cndmask_b32_e64 v23, 0, v31, s[40:41]
	v_pk_mul_f32 v[18:19], v[18:19], s[76:77] op_sel_hi:[1,0]
	v_cndmask_b32_e64 v22, 0, v37, s[40:41]
	v_cvt_pk_f16_f32 v18, v18, v19
	ds_write_b32 v17, v18 offset:4096
	s_waitcnt lgkmcnt(1)
; DI void hyena_item(const Params& p, int l, int dpr, LAS unsigned char* lds) {
;     ...
; #pragma unroll 4
;     for (int r = 0; r < 16; ++r) { const int t = tid + NTHR * r; const hc y0 = X0[XI(t)], y1 = X1[XI(t)];
;         const float yv[4] = {(float)y0.x, (float)y0.y, (float)y1.x, (float)y1.y};
;         float z[4];
; #pragma unroll
;         for (int c = 0; c < 4; ++c) z[c] = yv[c] * (1.0f / 64.0f) * conv3(bint + (size_t)(1024 + a + c) * S, t, w[c][0], w[c][1], w[c][2]) * 0.25f;
;         X0[XI(t)] = (hc){(_Float16)z[0], (_Float16)z[1]}; X1[XI(t)] = (hc){(_Float16)z[2], (_Float16)z[3]};
;         X0[XI(t + 8192)] = hzero; X1[XI(t + 8192)] = hzero; }
;     __syncthreads();
	v_cvt_f32_f16_e32 v18, v32
	v_cvt_f32_f16_sdwa v19, v32 dst_sel:DWORD dst_unused:UNUSED_PAD src0_sel:WORD_1
	v_pk_mul_f32 v[22:23], v[2:3], v[22:23]
	v_pk_mul_f32 v[18:19], v[18:19], s[38:39] op_sel_hi:[1,0]
	v_pk_fma_f32 v[22:23], v[6:7], v[28:29], v[22:23]
	s_nop 0
	v_pk_fma_f32 v[22:23], v[10:11], v[24:25], v[22:23]
	s_nop 0
	v_pk_mul_f32 v[18:19], v[18:19], v[22:23]
	s_nop 0
	v_pk_mul_f32 v[18:19], v[18:19], s[76:77] op_sel_hi:[1,0]
	s_nop 0
	v_cvt_pk_f16_f32 v17, v18, v19
	ds_write_b32 v13, v17 offset:4096
	v_add_u32_e32 v13, 0x2400, v16
	v_ashrrev_i32_e32 v17, 4, v13
	v_ashrrev_i32_e32 v13, 8, v13
	v_add_u32_e32 v13, v17, v13
	v_add_lshl_u32 v13, v16, v13, 2
	v_add_u32_e32 v18, 0x600, v16
	v_add_u32_e32 v17, 0, v13
	v_add_u32_e32 v13, s66, v13
	v_ashrrev_i32_e32 v19, 31, v18
	v_max_i32_e32 v96, 1, v18
	v_min_i32_e32 v22, 0x1ffe, v18
	ds_write_b32 v17, v97 offset:36864
	ds_write_b32 v13, v97 offset:36864
	v_ashrrev_i32_e32 v13, 4, v18
	v_ashrrev_i32_e32 v17, 8, v18
	v_cmp_lt_i32_e64 s[40:41], 0, v18
	v_cmp_gt_i32_e64 s[42:43], s29, v18
	v_ashrrev_i32_e32 v23, 31, v22
	v_lshlrev_b64 v[18:19], 2, v[18:19]
	v_lshlrev_b64 v[26:27], 2, v[96:97]
	v_lshl_add_u64 v[24:25], s[26:27], 0, v[18:19]
	v_lshl_add_u64 v[28:29], s[26:27], 0, v[26:27]
	v_lshlrev_b64 v[22:23], 2, v[22:23]
	v_mov_b32_e32 v24, v136
	v_lshl_add_u64 v[30:31], s[20:21], 0, v[26:27]
	v_mov_b32_e32 v33, v137
	v_lshl_add_u64 v[28:29], s[26:27], 0, v[22:23]
	v_mov_b32_e32 v34, v138
	v_lshl_add_u64 v[28:29], s[22:23], 0, v[18:19]
	v_mov_b32_e32 v25, v139
	v_lshl_add_u64 v[28:29], s[22:23], 0, v[26:27]
	v_mov_b32_e32 v35, v140
	v_lshl_add_u64 v[28:29], s[22:23], 0, v[22:23]
	v_mov_b32_e32 v36, v141
	v_lshl_add_u64 v[28:29], s[20:21], 0, v[18:19]
	v_lshl_add_u64 v[18:19], s[24:25], 0, v[18:19]
	v_mov_b32_e32 v28, v142
	v_add_u32_e32 v13, v13, v17
	v_mov_b32_e32 v37, v143
	v_mov_b32_e32 v29, v145
	v_lshl_add_u64 v[30:31], s[20:21], 0, v[22:23]
	v_lshl_add_u64 v[18:19], s[24:25], 0, v[26:27]
	v_mov_b32_e32 v30, v144
	v_add_lshl_u32 v13, v16, v13, 2
	v_mov_b32_e32 v31, v146
	v_lshl_add_u64 v[18:19], s[24:25], 0, v[22:23]
	v_mov_b32_e32 v38, v147
	v_add_u32_e32 v17, 0, v13
	ds_read_b32 v21, v17 offset:6144
	v_add_u32_e32 v13, s66, v13
	ds_read_b32 v32, v13 offset:6144
	s_waitcnt lgkmcnt(1)
	v_cvt_f32_f16_e32 v18, v21
	v_cvt_f32_f16_sdwa v19, v21 dst_sel:DWORD dst_unused:UNUSED_PAD src0_sel:WORD_1
	v_pk_mul_f32 v[18:19], v[18:19], s[38:39] op_sel_hi:[1,0]
	s_nop 0
	v_cndmask_b32_e64 v22, 0, v33, s[40:41]
	s_nop 0
	v_cndmask_b32_e64 v26, 0, v34, s[42:43]
	s_nop 0
	v_cndmask_b32_e64 v23, 0, v35, s[40:41]
	v_pk_mul_f32 v[22:23], v[0:1], v[22:23]
	s_nop 0
	v_cndmask_b32_e64 v27, 0, v36, s[42:43]
	v_pk_fma_f32 v[22:23], v[4:5], v[24:25], v[22:23]
	s_nop 0
	v_cndmask_b32_e64 v24, 0, v30, s[42:43]
	v_pk_fma_f32 v[22:23], v[8:9], v[26:27], v[22:23]
	s_nop 0
	v_cndmask_b32_e64 v25, 0, v38, s[42:43]
	v_pk_mul_f32 v[18:19], v[18:19], v[22:23]
	v_cndmask_b32_e64 v23, 0, v31, s[40:41]
	v_pk_mul_f32 v[18:19], v[18:19], s[76:77] op_sel_hi:[1,0]
	v_cndmask_b32_e64 v22, 0, v37, s[40:41]
	v_cvt_pk_f16_f32 v18, v18, v19
	ds_write_b32 v17, v18 offset:6144
	s_waitcnt lgkmcnt(1)
	v_cvt_f32_f16_e32 v18, v32
	v_cvt_f32_f16_sdwa v19, v32 dst_sel:DWORD dst_unused:UNUSED_PAD src0_sel:WORD_1
	v_pk_mul_f32 v[22:23], v[2:3], v[22:23]
	v_pk_mul_f32 v[18:19], v[18:19], s[38:39] op_sel_hi:[1,0]
	v_pk_fma_f32 v[22:23], v[6:7], v[28:29], v[22:23]
	s_nop 0
	v_pk_fma_f32 v[22:23], v[10:11], v[24:25], v[22:23]
	s_nop 0
	v_pk_mul_f32 v[18:19], v[18:19], v[22:23]
	s_nop 0
	v_pk_mul_f32 v[18:19], v[18:19], s[76:77] op_sel_hi:[1,0]
	s_nop 0
	v_cvt_pk_f16_f32 v17, v18, v19
	ds_write_b32 v13, v17 offset:6144
	v_add_u32_e32 v13, 0x2600, v16
	v_ashrrev_i32_e32 v17, 4, v13
	v_ashrrev_i32_e32 v13, 8, v13
	v_add_u32_e32 v13, v17, v13
	v_add_lshl_u32 v13, v16, v13, 2
	v_add_u32_e32 v16, 0, v13
	v_add_u32_e32 v13, s66, v13
	ds_write_b32 v16, v97 offset:38912
	ds_write_b32 v13, v97 offset:38912
	s_cbranch_scc0 .LBB0_699
	v_mov_b32_e32 v0, v12
	s_waitcnt lgkmcnt(0)
	s_barrier
	s_nop 0
	v_cmp_gt_i32_e64 s[40:41], s45, v0
	s_and_saveexec_b64 s[20:21], s[40:41]
	s_movk_i32 s10, 0xc000
	s_movk_i32 s12, 0xdff
	s_cbranch_execz .LBB0_703
	v_lshlrev_b32_e32 v1, 2, v0
	s_mov_b64 s[22:23], 0
